# attention: row-max all-reduce via v_permlane16/32_swap instead of ds_bpermute (on top of v11)
# speedup vs baseline: 1.0094x; 1.0018x over previous
; __device__ __forceinline__ void attn_phase(unsigned char* lds, const Params& p, int jl, const bf16_t* proj, bf16_t* mix, int blk, int G, int tid) {
;     ...
;             if (t >= w_lo && t <= w_hi) {
;                 const bf16_t* ks = KS + buf * (64 * 136); const bf16_t* vt = VT + buf * (128 * 72);
;                 const int nvk = (samp && t == 8) ? 32 : 64;
;                 f32x4 s[2][4];
; #pragma unroll
;                 for (int qt = 0; qt < 2; ++qt)
; #pragma unroll
;                     for (int kt = 0; kt < 4; ++kt) s[qt][kt] = (f32x4){0.f, 0.f, 0.f, 0.f};
; #pragma unroll
;                 for (int kh2 = 0; kh2 < 2; ++kh2) { bf16x8 kf[2][4];
; #pragma unroll
;                     for (int kt = 0; kt < 2; ++kt)
; #pragma unroll
;                         for (int k4 = 0; k4 < 4; ++k4) kf[kt][k4] = *(const bf16x8*)(ks + ((kh2 * 2 + kt) * 16 + fr) * 136 + k4 * 32 + fq * 8);
;                     __builtin_amdgcn_sched_barrier(0);
; #pragma unroll
;                     for (int k4 = 0; k4 < 4; ++k4)
; #pragma unroll
;                         for (int kt = 0; kt < 2; ++kt)
; #pragma unroll
;                             for (int qt = 0; qt < 2; ++qt) s[qt][kh2 * 2 + kt] = MFMA16(kf[kt][k4], qf[qt][k4], s[qt][kh2 * 2 + kt]);
;                     __builtin_amdgcn_sched_barrier(0); }
;                 bf16x8 vf[4][2][2];
;     ...
;                 ATT_VLOAD(0);
;                 __builtin_amdgcn_sched_barrier(0);
;                 bf16x8 pb[2][2];
; #pragma unroll
;                 for (int qt = 0; qt < 2; ++qt) {
;                     const float* bp = BIAS + (575 - (qpos0 + qt * 16 - t * 64 - fq * 4));
; #pragma unroll
;                     for (int kt = 0; kt < 4; ++kt) { const f32x4 bv = {bp[kt * 16], bp[kt * 16 + 1], bp[kt * 16 + 2], bp[kt * 16 + 3]}; s[qt][kt] = s[qt][kt] * SC2 + bv; }
;                     if (nvk < 64) {
; #pragma unroll
;                         for (int kt = 0; kt < 4; ++kt)
; #pragma unroll
;                             for (int j = 0; j < 4; ++j) if (kt * 16 + fq * 4 + j >= nvk) s[qt][kt][j] = NEG_INF; }
;                     float mx;
;                     { const f32x4 m01 = __builtin_elementwise_max(s[qt][0], s[qt][1]), m23 = __builtin_elementwise_max(s[qt][2], s[qt][3]), m4 = __builtin_elementwise_max(m01, m23);
;                       mx = fmaxf(fmaxf(m4[0], m4[1]), fmaxf(m4[2], m4[3])); }
.LBB0_205:
	v_cmp_ge_i32_e32 vcc, s47, v202
	v_cmp_le_i32_e64 s[4:5], s47, v203
	s_and_b32 s20, s35, 1
	s_and_b64 s[4:5], vcc, s[4:5]
	s_and_saveexec_b64 s[18:19], s[4:5]
	s_cbranch_execz .LBB0_211
	s_mul_i32 s4, s20, 0x4400
	v_add_u32_e32 v0, s4, v195
	ds_read_b128 v[116:119], v0
	ds_read_b128 v[120:123], v0 offset:64
	ds_read_b128 v[124:127], v0 offset:128
	ds_read_b128 v[128:131], v0 offset:192
	ds_read_b128 v[132:135], v0 offset:4352
	ds_read_b128 v[136:139], v0 offset:4416
	ds_read_b128 v[140:143], v0 offset:4480
	ds_read_b128 v[144:147], v0 offset:4544
	s_cmp_eq_u32 s47, 8
	s_mul_i32 s21, s20, 0x4800
	s_cselect_b64 s[4:5], -1, 0
	s_and_b64 s[4:5], s[6:7], s[4:5]
	s_add_i32 s21, s21, 0
	s_waitcnt lgkmcnt(7)
	v_mfma_f32_16x16x32_bf16 v[168:171], v[116:119], v[52:55], 0
	v_mfma_f32_16x16x32_bf16 v[116:119], v[116:119], v[76:79], 0
	s_waitcnt lgkmcnt(3)
	v_mfma_f32_16x16x32_bf16 v[172:175], v[132:135], v[52:55], 0
	v_mfma_f32_16x16x32_bf16 v[132:135], v[132:135], v[76:79], 0
	v_mfma_f32_16x16x32_bf16 v[168:171], v[120:123], v[56:59], v[168:171]
	v_mfma_f32_16x16x32_bf16 v[116:119], v[120:123], v[68:71], v[116:119]
	s_waitcnt lgkmcnt(2)
	v_mfma_f32_16x16x32_bf16 v[120:123], v[136:139], v[56:59], v[172:175]
	v_mfma_f32_16x16x32_bf16 v[132:135], v[136:139], v[68:71], v[132:135]
	v_mfma_f32_16x16x32_bf16 v[136:139], v[124:127], v[60:63], v[168:171]
	v_mfma_f32_16x16x32_bf16 v[116:119], v[124:127], v[72:75], v[116:119]
	s_waitcnt lgkmcnt(1)
	v_mfma_f32_16x16x32_bf16 v[120:123], v[140:143], v[60:63], v[120:123]
	v_mfma_f32_16x16x32_bf16 v[124:127], v[140:143], v[72:75], v[132:135]
	v_mfma_f32_16x16x32_bf16 v[170:173], v[128:131], v[64:67], v[136:139]
	v_mfma_f32_16x16x32_bf16 v[132:135], v[128:131], v[80:83], v[116:119]
	s_waitcnt lgkmcnt(0)
	v_mfma_f32_16x16x32_bf16 v[182:185], v[144:147], v[64:67], v[120:123]
	v_mfma_f32_16x16x32_bf16 v[136:139], v[144:147], v[80:83], v[124:127]
	ds_read_b128 v[116:119], v0 offset:8704
	s_nop 0
	ds_read_b128 v[120:123], v0 offset:8768
	ds_read_b128 v[124:127], v0 offset:8832
	ds_read_b128 v[128:131], v0 offset:8896
	ds_read_b128 v[140:143], v0 offset:13056
	ds_read_b128 v[144:147], v0 offset:13120
	ds_read_b128 v[174:177], v0 offset:13184
	ds_read_b128 v[178:181], v0 offset:13248
	s_waitcnt lgkmcnt(7)
	v_mfma_f32_16x16x32_bf16 v[216:219], v[116:119], v[52:55], 0
	v_mfma_f32_16x16x32_bf16 v[116:119], v[116:119], v[76:79], 0
	s_waitcnt lgkmcnt(3)
	v_mfma_f32_16x16x32_bf16 v[220:223], v[140:143], v[52:55], 0
	v_mfma_f32_16x16x32_bf16 v[140:143], v[140:143], v[76:79], 0
	v_mfma_f32_16x16x32_bf16 v[216:219], v[120:123], v[56:59], v[216:219]
	v_mfma_f32_16x16x32_bf16 v[116:119], v[120:123], v[68:71], v[116:119]
	s_waitcnt lgkmcnt(2)
	v_mfma_f32_16x16x32_bf16 v[140:143], v[144:147], v[68:71], v[140:143]
	v_mfma_f32_16x16x32_bf16 v[120:123], v[144:147], v[56:59], v[220:223]
	v_mfma_f32_16x16x32_bf16 v[144:147], v[124:127], v[60:63], v[216:219]
	v_mfma_f32_16x16x32_bf16 v[116:119], v[124:127], v[72:75], v[116:119]
	s_waitcnt lgkmcnt(1)
	v_mfma_f32_16x16x32_bf16 v[124:127], v[174:177], v[72:75], v[140:143]
	v_mfma_f32_16x16x32_bf16 v[120:123], v[174:177], v[60:63], v[120:123]
	v_mfma_f32_16x16x32_bf16 v[222:225], v[128:131], v[64:67], v[144:147]
	v_mfma_f32_16x16x32_bf16 v[144:147], v[128:131], v[80:83], v[116:119]
	s_waitcnt lgkmcnt(0)
	v_mfma_f32_16x16x32_bf16 v[140:143], v[178:181], v[80:83], v[124:127]
	v_mfma_f32_16x16x32_bf16 v[226:229], v[178:181], v[64:67], v[120:123]
	v_add3_u32 v0, s21, v160, v161
	v_add_u32_e32 v2, 0x8800, v0
	v_add_u32_e32 v0, 0x9000, v0
	ds_read_b64 v[124:125], v2
	ds_read_b64 v[126:127], v2 offset:32
	ds_read_b64 v[120:121], v2 offset:64
	ds_read_b64 v[122:123], v2 offset:96
	ds_read_b64 v[128:129], v0 offset:256
	ds_read_b64 v[130:131], v0 offset:288
	ds_read_b64 v[116:117], v0 offset:320
	ds_read_b64 v[118:119], v0 offset:352
	v_and_b32_e32 v2, 64, v213
	ds_read2_b32 v[174:175], v204 offset0:16 offset1:17
	ds_read2_b32 v[176:177], v204 offset0:18 offset1:19
	ds_read2_b32 v[178:179], v204 offset0:32 offset1:33
	ds_read2_b32 v[180:181], v204 offset0:34 offset1:35
	v_xor_b32_e32 v0, 16, v213
	v_add_u32_e32 v2, 64, v2
	v_cmp_lt_i32_e32 vcc, v0, v2
	s_mov_b32 s28, 0x3e0293ee
	s_waitcnt lgkmcnt(2)
	v_pk_fma_f32 v[168:169], v[172:173], s[28:29], v[176:177] op_sel_hi:[1,0,1]
	v_cndmask_b32_e32 v0, v213, v0, vcc
	v_lshlrev_b32_e32 v219, 2, v0
	v_xor_b32_e32 v0, 32, v213
	v_cmp_lt_i32_e32 vcc, v0, v2
	v_pk_fma_f32 v[2:3], v[170:171], s[28:29], v[174:175] op_sel_hi:[1,0,1]
	s_waitcnt lgkmcnt(0)
	v_pk_fma_f32 v[172:173], v[184:185], s[28:29], v[180:181] op_sel_hi:[1,0,1]
	v_pk_fma_f32 v[170:171], v[182:183], s[28:29], v[178:179] op_sel_hi:[1,0,1]
	ds_read2_b32 v[182:183], v204 offset0:48 offset1:49
	ds_read2_b32 v[184:185], v204 offset0:50 offset1:51
	ds_read2_b32 v[210:211], v204 offset0:64 offset1:65
	ds_read2_b32 v[216:217], v204 offset0:66 offset1:67
	v_cndmask_b32_e32 v0, v213, v0, vcc
	v_lshlrev_b32_e32 v220, 2, v0
	s_waitcnt lgkmcnt(3)
	v_pk_fma_f32 v[188:189], v[222:223], s[28:29], v[182:183] op_sel_hi:[1,0,1]
	s_waitcnt lgkmcnt(2)
	v_pk_fma_f32 v[152:153], v[224:225], s[28:29], v[184:185] op_sel_hi:[1,0,1]
	s_waitcnt lgkmcnt(0)
	v_pk_fma_f32 v[216:217], v[228:229], s[28:29], v[216:217] op_sel_hi:[1,0,1]
	v_cndmask_b32_e64 v222, v152, v214, s[4:5]
	v_cndmask_b32_e64 v216, v216, v214, s[4:5]
	v_pk_fma_f32 v[210:211], v[226:227], s[28:29], v[210:211] op_sel_hi:[1,0,1]
	v_cndmask_b32_e64 v215, v217, v214, s[4:5]
	v_cndmask_b32_e64 v221, v153, v214, s[4:5]
	v_cndmask_b32_e64 v218, v210, v214, s[4:5]
	v_cndmask_b32_e64 v224, v188, v214, s[4:5]
	v_cndmask_b32_e64 v217, v211, v214, s[4:5]
	v_cndmask_b32_e64 v223, v189, v214, s[4:5]
	v_max_f32_e32 v0, v222, v216
	v_max_f32_e32 v152, v221, v215
	v_max_f32_e32 v153, v224, v218
	v_max_f32_e32 v187, v223, v217
	v_max3_f32 v152, v169, v173, v152
	v_max3_f32 v0, v168, v172, v0
	v_max3_f32 v187, v3, v171, v187
	v_max3_f32 v153, v2, v170, v153
	v_max_f32_e32 v0, v0, v152
	v_max3_f32 v0, v153, v187, v0
	s_waitcnt lgkmcnt(0)
	v_mov_b32_e32 v152, v0
	s_nop 1
	v_permlane16_swap_b32_e32 v152, v0
	v_max_f32_e32 v0, v0, v152
	v_mov_b32_e32 v152, v0
	s_nop 1
	v_permlane32_swap_b32_e32 v152, v0
	v_max_f32_e32 v0, v0, v152
	v_sub_f32_e32 v152, v0, v186
	v_cmp_lt_f32_e32 vcc, 4.0, v152
	s_nop 1
	v_cndmask_b32_e32 v207, v186, v0, vcc
	v_sub_f32_e32 v0, v186, v207
	v_exp_f32_e32 v0, v0
	s_nop 0
	v_cmp_neq_f32_e32 vcc, 1.0, v0
	s_cbranch_vccz .LBB0_208
; __device__ __forceinline__ void attn_phase(unsigned char* lds, const Params& p, int jl, const bf16_t* proj, bf16_t* mix, int blk, int G, int tid) {
;     ...
;                     const float* bp = BIAS + (575 - (qpos0 + qt * 16 - t * 64 - fq * 4));
; #pragma unroll
;                     for (int kt = 0; kt < 4; ++kt) { const f32x4 bv = {bp[kt * 16], bp[kt * 16 + 1], bp[kt * 16 + 2], bp[kt * 16 + 3]}; s[qt][kt] = s[qt][kt] * SC2 + bv; }
;                     if (nvk < 64) {
; #pragma unroll
;                         for (int kt = 0; kt < 4; ++kt)
; #pragma unroll
;                             for (int j = 0; j < 4; ++j) if (kt * 16 + fq * 4 + j >= nvk) s[qt][kt][j] = NEG_INF; }
;                     float mx;
;                     { const f32x4 m01 = __builtin_elementwise_max(s[qt][0], s[qt][1]), m23 = __builtin_elementwise_max(s[qt][2], s[qt][3]), m4 = __builtin_elementwise_max(m01, m23);
;                       mx = fmaxf(fmaxf(m4[0], m4[1]), fmaxf(m4[2], m4[3])); }
;                     mx = fmaxf(mx, __shfl_xor(mx, 16)); mx = fmaxf(mx, __shfl_xor(mx, 32));
;                     const float m_new = fmaxf(m_run[qt], mx), alpha = __builtin_amdgcn_exp2f(m_run[qt] - m_new);
; #pragma unroll
;                     for (int kt = 0; kt < 4; ++kt) { s[qt][kt] = s[qt][kt] - m_new;
; #pragma unroll
;                         for (int j = 0; j < 4; ++j) s[qt][kt][j] = __builtin_amdgcn_exp2f(s[qt][kt][j]); }
;                     const f32x4 sv4 = (s[qt][0] + s[qt][1]) + (s[qt][2] + s[qt][3]);
;                     const float ps = (sv4[0] + sv4[1]) + (sv4[2] + sv4[3]);
;                     l_run[qt] = l_run[qt] * alpha + ps; m_run[qt] = m_new;
;                     if (__any(alpha != 1.f)) {
; #pragma unroll
;                         for (int dt = 0; dt < 8; ++dt) o[qt][dt] = o[qt][dt] * alpha; }
	v_pk_mul_f32 v[106:107], v[106:107], v[0:1] op_sel_hi:[1,0]
	v_pk_mul_f32 v[104:105], v[104:105], v[0:1] op_sel_hi:[1,0]
	v_pk_mul_f32 v[98:99], v[98:99], v[0:1] op_sel_hi:[1,0]
	v_pk_mul_f32 v[96:97], v[96:97], v[0:1] op_sel_hi:[1,0]
	v_pk_mul_f32 v[90:91], v[90:91], v[0:1] op_sel_hi:[1,0]
	v_pk_mul_f32 v[88:89], v[88:89], v[0:1] op_sel_hi:[1,0]
	v_pk_mul_f32 v[86:87], v[86:87], v[0:1] op_sel_hi:[1,0]
	v_pk_mul_f32 v[84:85], v[84:85], v[0:1] op_sel_hi:[1,0]
	v_pk_mul_f32 v[50:51], v[50:51], v[0:1] op_sel_hi:[1,0]
	v_pk_mul_f32 v[48:49], v[48:49], v[0:1] op_sel_hi:[1,0]
	v_pk_mul_f32 v[46:47], v[46:47], v[0:1] op_sel_hi:[1,0]
	v_pk_mul_f32 v[44:45], v[44:45], v[0:1] op_sel_hi:[1,0]
	v_pk_mul_f32 v[42:43], v[42:43], v[0:1] op_sel_hi:[1,0]
	v_pk_mul_f32 v[40:41], v[40:41], v[0:1] op_sel_hi:[1,0]
	v_pk_mul_f32 v[38:39], v[38:39], v[0:1] op_sel_hi:[1,0]
	v_pk_mul_f32 v[36:37], v[36:37], v[0:1] op_sel_hi:[1,0]
.LBB0_208:
	ds_read2_b32 v[152:153], v204 offset0:2 offset1:3
	ds_read2_b32 v[186:187], v204 offset1:1
	v_pk_fma_f32 v[174:175], v[136:137], s[28:29], v[174:175] op_sel_hi:[1,0,1]
	v_pk_fma_f32 v[136:137], v[142:143], s[28:29], v[184:185] op_sel_hi:[1,0,1]
	v_pk_fma_f32 v[176:177], v[138:139], s[28:29], v[176:177] op_sel_hi:[1,0,1]
	v_cndmask_b32_e64 v143, v136, v214, s[4:5]
	s_waitcnt lgkmcnt(0)
	v_pk_fma_f32 v[186:187], v[132:133], s[28:29], v[186:187] op_sel_hi:[1,0,1]
	v_pk_fma_f32 v[132:133], v[146:147], s[28:29], v[180:181] op_sel_hi:[1,0,1]
	v_pk_fma_f32 v[188:189], v[134:135], s[28:29], v[152:153] op_sel_hi:[1,0,1]
	v_cndmask_b32_e64 v147, v132, v214, s[4:5]
	v_pk_fma_f32 v[134:135], v[144:145], s[28:29], v[178:179] op_sel_hi:[1,0,1]
	v_pk_fma_f32 v[138:139], v[140:141], s[28:29], v[182:183] op_sel_hi:[1,0,1]
	v_cndmask_b32_e64 v142, v137, v214, s[4:5]
	v_cndmask_b32_e64 v146, v133, v214, s[4:5]
	v_cndmask_b32_e64 v145, v138, v214, s[4:5]
	v_cndmask_b32_e64 v179, v134, v214, s[4:5]
	v_cndmask_b32_e64 v144, v139, v214, s[4:5]
	v_cndmask_b32_e64 v178, v135, v214, s[4:5]
	v_max_f32_e32 v132, v147, v143
	v_max_f32_e32 v133, v146, v142
	v_max_f32_e32 v134, v179, v145
	v_max_f32_e32 v135, v178, v144
	v_max3_f32 v133, v189, v177, v133
	v_max3_f32 v132, v188, v176, v132
	v_max3_f32 v135, v187, v175, v135
	v_max3_f32 v134, v186, v174, v134
	v_max_f32_e32 v132, v132, v133
	v_max3_f32 v132, v134, v135, v132
	s_waitcnt lgkmcnt(0)
	v_mov_b32_e32 v133, v132
	s_nop 1
	v_permlane16_swap_b32_e32 v133, v132
	v_max_f32_e32 v132, v132, v133
	v_mov_b32_e32 v133, v132
	s_nop 1
	v_permlane32_swap_b32_e32 v133, v132
	v_max_f32_e32 v132, v132, v133
	v_sub_f32_e32 v133, v132, v206
	v_cmp_lt_f32_e32 vcc, 4.0, v133
	s_nop 1
	v_cndmask_b32_e32 v141, v206, v132, vcc
	v_sub_f32_e32 v132, v206, v141
	v_exp_f32_e32 v140, v132
	s_nop 0
	v_cmp_neq_f32_e32 vcc, 1.0, v140
	s_cbranch_vccz .LBB0_210
	v_pk_mul_f32 v[34:35], v[34:35], v[140:141] op_sel_hi:[1,0]
	v_pk_mul_f32 v[32:33], v[32:33], v[140:141] op_sel_hi:[1,0]
	v_pk_mul_f32 v[30:31], v[30:31], v[140:141] op_sel_hi:[1,0]
	v_pk_mul_f32 v[28:29], v[28:29], v[140:141] op_sel_hi:[1,0]
	v_pk_mul_f32 v[26:27], v[26:27], v[140:141] op_sel_hi:[1,0]
	v_pk_mul_f32 v[24:25], v[24:25], v[140:141] op_sel_hi:[1,0]
	v_pk_mul_f32 v[22:23], v[22:23], v[140:141] op_sel_hi:[1,0]
	v_pk_mul_f32 v[20:21], v[20:21], v[140:141] op_sel_hi:[1,0]
	v_pk_mul_f32 v[18:19], v[18:19], v[140:141] op_sel_hi:[1,0]
	v_pk_mul_f32 v[16:17], v[16:17], v[140:141] op_sel_hi:[1,0]
	v_pk_mul_f32 v[14:15], v[14:15], v[140:141] op_sel_hi:[1,0]
	v_pk_mul_f32 v[12:13], v[12:13], v[140:141] op_sel_hi:[1,0]
	v_pk_mul_f32 v[10:11], v[10:11], v[140:141] op_sel_hi:[1,0]
	v_pk_mul_f32 v[8:9], v[8:9], v[140:141] op_sel_hi:[1,0]
	v_pk_mul_f32 v[6:7], v[6:7], v[140:141] op_sel_hi:[1,0]
	v_pk_mul_f32 v[4:5], v[4:5], v[140:141] op_sel_hi:[1,0]
